# GLA chain loop: cross-row sum-of-squares reductions via v_permlane16_swap/v_permlane32_swap instead of two serialized ds_bpermute round trips per block (same add order)
# speedup vs baseline: 1.0145x; 1.0027x over previous
; __device__ __forceinline__ unsigned pk2(float lo, float hi) { f32x2 v = {lo, hi}; bf16x2_t b = __builtin_convertvector(v, bf16x2_t); return __builtin_bit_cast(unsigned, b); }
; __device__ __forceinline__ void gla_prompt_unit(const Ctx& P, int l, int b, int h, int eh, LAS unsigned char* lds) {
;     ...
;         for (int tt = 0; tt < 4; ++tt) { const int t = 16 * tt + fr;
;             float p = (o[tt][0] * o[tt][0] + o[tt][1] * o[tt][1]) + (o[tt][2] * o[tt][2] + o[tt][3] * o[tt][3]);
;             p += __shfl_xor(p, 16); p += __shfl_xor(p, 32);
;             if (t < L) { const size_t row = (size_t)(row0 + t);
;                 u32x2 ow; ow.x = pk2(o[tt][0], o[tt][1]); ow.y = pk2(o[tt][2], o[tt][3]);
;                 *(u32x2*)(OG + row * D + h * 256 + e0w + fq * 4) = ow;
;                 if (fq == 0) GSS[(row * 4 + h) * 16 + eh * 8 + w] = p; } }
.LBB0_584:
	s_and_saveexec_b64 s[22:23], s[38:39]
	v_lshl_add_u32 v18, s60, 9, v114
	ds_write_b32 v18, v111
	s_or_b64 exec, exec, s[22:23]
	v_mul_f32_e32 v18, v71, v71
	v_mul_f32_e32 v19, v73, v73
	v_fmac_f32_e32 v18, v70, v70
	v_fmac_f32_e32 v19, v72, v72
	v_add_f32_e32 v19, v18, v19
	v_mov_b32_e32 v244, v19
	v_mov_b32_e32 v245, v19
	v_add_u32_e32 v20, s68, v116
	v_add_u32_e32 v18, 16, v20
	v_cvt_pk_bf16_f32 v24, v70, v71
	v_cvt_pk_bf16_f32 v25, v72, v73
	v_permlane16_swap_b32 v244, v245
	v_add_f32_e32 v21, v19, v245
	v_mov_b32_e32 v246, v21
	v_mov_b32_e32 v247, v21
	v_ashrrev_i32_e32 v19, 31, v18
	v_lshlrev_b64 v[70:71], 11, v[18:19]
	v_lshl_add_u64 v[70:71], v[74:75], 0, v[70:71]
	global_store_dwordx2 v[70:71], v[24:25], off
	v_permlane32_swap_b32 v246, v247
	s_and_saveexec_b64 s[22:23], s[40:41]
	s_cbranch_execz .LBB0_588
	v_lshlrev_b64 v[18:19], 8, v[18:19]
	v_lshl_add_u64 v[18:19], s[8:9], 0, v[18:19]
	v_add_f32_e32 v21, v21, v247
	global_store_dword v[18:19], v21, off
.LBB0_588:
	s_or_b64 exec, exec, s[22:23]
	v_mul_f32_e32 v18, v67, v67
	v_mul_f32_e32 v19, v69, v69
	v_fmac_f32_e32 v18, v66, v66
	v_fmac_f32_e32 v19, v68, v68
	v_add_f32_e32 v21, v18, v19
	v_mov_b32_e32 v244, v21
	v_mov_b32_e32 v245, v21
	v_add_u32_e32 v18, 32, v20
	v_ashrrev_i32_e32 v19, 31, v18
	v_cvt_pk_bf16_f32 v24, v66, v67
	v_lshlrev_b64 v[66:67], 11, v[18:19]
	v_permlane16_swap_b32 v244, v245
	v_add_f32_e32 v21, v21, v245
	v_mov_b32_e32 v246, v21
	v_mov_b32_e32 v247, v21
	v_cvt_pk_bf16_f32 v25, v68, v69
	v_lshl_add_u64 v[66:67], v[74:75], 0, v[66:67]
	global_store_dwordx2 v[66:67], v[24:25], off
	v_permlane32_swap_b32 v246, v247
	s_and_saveexec_b64 s[22:23], s[40:41]
	s_cbranch_execz .LBB0_590
	v_lshlrev_b64 v[18:19], 8, v[18:19]
	v_lshl_add_u64 v[18:19], s[8:9], 0, v[18:19]
	v_add_f32_e32 v21, v21, v247
	global_store_dword v[18:19], v21, off
.LBB0_590:
	s_or_b64 exec, exec, s[22:23]
	v_mul_f32_e32 v18, v63, v63
	v_mul_f32_e32 v19, v65, v65
	v_fmac_f32_e32 v18, v62, v62
	v_fmac_f32_e32 v19, v64, v64
	v_add_f32_e32 v21, v18, v19
	v_mov_b32_e32 v244, v21
	v_mov_b32_e32 v245, v21
	v_add_u32_e32 v18, 48, v20
	v_ashrrev_i32_e32 v19, 31, v18
	v_cvt_pk_bf16_f32 v24, v62, v63
	v_lshlrev_b64 v[62:63], 11, v[18:19]
	v_permlane16_swap_b32 v244, v245
	v_add_f32_e32 v21, v21, v245
	v_mov_b32_e32 v246, v21
	v_mov_b32_e32 v247, v21
	v_cvt_pk_bf16_f32 v25, v64, v65
	v_lshl_add_u64 v[62:63], v[74:75], 0, v[62:63]
	global_store_dwordx2 v[62:63], v[24:25], off
	v_permlane32_swap_b32 v246, v247
	s_and_saveexec_b64 s[22:23], s[40:41]
	s_cbranch_execz .LBB0_592
	v_lshlrev_b64 v[18:19], 8, v[18:19]
	v_lshl_add_u64 v[18:19], s[8:9], 0, v[18:19]
	v_add_f32_e32 v21, v21, v247
	global_store_dword v[18:19], v21, off
.LBB0_592:
	s_or_b64 exec, exec, s[22:23]
	v_mul_f32_e32 v18, v59, v59
	v_mul_f32_e32 v19, v61, v61
	v_fmac_f32_e32 v18, v58, v58
	v_fmac_f32_e32 v19, v60, v60
	v_add_f32_e32 v21, v18, v19
	v_mov_b32_e32 v244, v21
	v_mov_b32_e32 v245, v21
	v_add_u32_e32 v18, 64, v20
	v_ashrrev_i32_e32 v19, 31, v18
	v_lshlrev_b64 v[24:25], 11, v[18:19]
	v_cvt_pk_bf16_f32 v23, v60, v61
	v_permlane16_swap_b32 v244, v245
	v_add_f32_e32 v20, v21, v245
	v_mov_b32_e32 v246, v20
	v_mov_b32_e32 v247, v20
	v_cvt_pk_bf16_f32 v22, v58, v59
	v_lshl_add_u64 v[24:25], v[74:75], 0, v[24:25]
	global_store_dwordx2 v[24:25], v[22:23], off
	v_permlane32_swap_b32 v246, v247
	s_and_saveexec_b64 s[22:23], s[40:41]
	s_cbranch_execz .LBB0_594
	v_lshlrev_b64 v[18:19], 8, v[18:19]
	v_lshl_add_u64 v[18:19], s[8:9], 0, v[18:19]
	v_add_f32_e32 v20, v20, v247
	global_store_dword v[18:19], v20, off
